# EpiGU: one branch per tile to a straight-line copy of the eight row blocks when the row scales are cached (no per-block flag/branch/row-index code)
# speedup vs baseline: 1.0048x; 1.0009x over previous
;     __device__ __forceinline__ void operator()(const f32x4 (&acc)[2][2][4][2], const Unit& u, int wr, int wc, int fr, int fq) const {
;         const int row0 = u.pm * BM + wr * 64 + fr;
; #pragma unroll
;         for (int ai = 0; ai < 2; ++ai)
; #pragma unroll
;             for (int m = 0; m < 4; ++m) {
;                 const int row = row0 + ai * HALF + m * 16;
;                 float rs;
;                 if (rsc) rs = rsc[row - rbase];
.LBB0_745:
	v_subrev_u32_e32 v156, s60, v148
	s_andn2_b64 vcc, exec, s[26:27]
	v_lshl_add_u32 v156, v156, 2, s46
	s_cbranch_vccnz .LBB0_747
	ds_read_b32 v228, v156
	ds_read_b32 v229, v156 offset:64
	ds_read_b32 v230, v156 offset:128
	ds_read_b32 v231, v156 offset:192
	ds_read_b32 v232, v156 offset:512
	ds_read_b32 v233, v156 offset:576
	ds_read_b32 v234, v156 offset:640
	ds_read_b32 v235, v156 offset:704
	s_waitcnt lgkmcnt(0)
	v_mov_b32_e32 v150, v228
	s_branch .Lgu_fast

; __device__ __forceinline__ unsigned cvt_pk_bf16(float lo, float hi) { f32x2 v = {lo, hi}; return __builtin_bit_cast(unsigned, __builtin_convertvector(v, nbf16x2e)); }
;     __device__ __forceinline__ void operator()(const f32x4 (&acc)[2][2][4][2], const Unit& u, int wr, int wc, int fr, int fq) const {
;     ...
;         for (int ai = 0; ai < 2; ++ai)
; #pragma unroll
;             for (int m = 0; m < 4; ++m) {
;                 const int row = row0 + ai * HALF + m * 16;
;                 float rs;
;                 if (rsc) rs = rsc[row - rbase];
;                 else {
;                     const f32x4* pp = (const f32x4*)(part + (size_t)row * 16);
;                     const f32x4 p0 = pp[0], p1 = pp[1], p2 = pp[2], p3 = pp[3];
;                     const float ssq = ((p0[0] + p0[1]) + (p0[2] + p0[3])) + ((p1[0] + p1[1]) + (p1[2] + p1[3])) + ((p2[0] + p2[1]) + (p2[2] + p2[3])) + ((p3[0] + p3[1]) + (p3[2] + p3[3]));
;                     rs = __builtin_amdgcn_rsqf(ssq * (1.0f / 1024.0f) + 1e-6f);
;                 }
;                 float v[8];
; #pragma unroll
;                 for (int n = 0; n < 2; ++n)
; #pragma unroll
;                     for (int i = 0; i < 4; ++i) { const float g = acc[ai][0][m][n][i] * rs, up = acc[ai][1][m][n][i] * rs; v[4 * n + i] = g * __builtin_amdgcn_rcpf(1.0f + __expf(-g)) * up; }
;                 u32x4 w; w.x = cvt_pk_bf16(v[0], v[1]); w.y = cvt_pk_bf16(v[2], v[3]); w.z = cvt_pk_bf16(v[4], v[5]); w.w = cvt_pk_bf16(v[6], v[7]);
;                 *(u32x4*)(O + (size_t)row * 2816 + u.pn * HALF + wc * 32 + 8 * fq) = w;
.Lgu_done:
	s_cbranch_vccnz .LBB0_736
	s_andn2_b64 vcc, exec, s[10:11]
	s_cbranch_vccnz .LBB0_735
	s_barrier
	s_branch .LBB0_735
.Lgu_fast:
	s_lshl_b32 s24, s24, 7
	s_ashr_i32 s25, s24, 31
	v_mov_b64_e32 v[236:237], s[34:35]
	v_mad_u64_u32 v[236:237], s[26:27], v148, s68, v[236:237]
	v_lshl_add_u64 v[236:237], s[24:25], 1, v[236:237]
	v_lshl_add_u64 v[236:237], v[236:237], 0, s[4:5]
	v_lshl_add_u64 v[236:237], v[236:237], 0, v[138:139]
	v_pk_mul_f32 v[126:127], v[126:127], v[228:229] op_sel_hi:[1,0]
	v_pk_mul_f32 v[128:129], v[128:129], v[228:229] op_sel_hi:[1,0]
	v_pk_mul_f32 v[122:123], v[122:123], v[228:229] op_sel_hi:[1,0]
	v_pk_mul_f32 v[124:125], v[124:125], v[228:229] op_sel_hi:[1,0]
	v_pk_mul_f32 v[176:177], v[126:127], v[184:185] op_sel_hi:[1,0]
	v_pk_mul_f32 v[178:179], v[128:129], v[184:185] op_sel_hi:[1,0]
	v_pk_mul_f32 v[180:181], v[122:123], v[184:185] op_sel_hi:[1,0]
	v_pk_mul_f32 v[182:183], v[124:125], v[184:185] op_sel_hi:[1,0]
	v_exp_f32_e32 v176, v176
	v_exp_f32_e32 v177, v177
	v_exp_f32_e32 v178, v178
	v_exp_f32_e32 v179, v179
	v_exp_f32_e32 v180, v180
	v_exp_f32_e32 v181, v181
	v_exp_f32_e32 v182, v182
	v_exp_f32_e32 v183, v183
	v_pk_add_f32 v[176:177], v[176:177], v[186:187] op_sel_hi:[1,0]
	v_pk_add_f32 v[178:179], v[178:179], v[186:187] op_sel_hi:[1,0]
	v_pk_add_f32 v[180:181], v[180:181], v[186:187] op_sel_hi:[1,0]
	v_pk_add_f32 v[182:183], v[182:183], v[186:187] op_sel_hi:[1,0]
	v_rcp_f32_e32 v176, v176
	v_rcp_f32_e32 v177, v177
	v_rcp_f32_e32 v178, v178
	v_rcp_f32_e32 v179, v179
	v_rcp_f32_e32 v180, v180
	v_rcp_f32_e32 v181, v181
	v_rcp_f32_e32 v182, v182
	v_rcp_f32_e32 v183, v183
	v_pk_mul_f32 v[118:119], v[118:119], v[228:229] op_sel_hi:[1,0]
	v_pk_mul_f32 v[120:121], v[120:121], v[228:229] op_sel_hi:[1,0]
	v_pk_mul_f32 v[114:115], v[114:115], v[228:229] op_sel_hi:[1,0]
	v_pk_mul_f32 v[116:117], v[116:117], v[228:229] op_sel_hi:[1,0]
	v_pk_mul_f32 v[126:127], v[126:127], v[176:177]
	v_pk_mul_f32 v[128:129], v[128:129], v[178:179]
	v_pk_mul_f32 v[122:123], v[122:123], v[180:181]
	v_pk_mul_f32 v[124:125], v[124:125], v[182:183]
	v_pk_mul_f32 v[118:119], v[118:119], v[126:127]
	v_pk_mul_f32 v[120:121], v[120:121], v[128:129]
	v_pk_mul_f32 v[122:123], v[114:115], v[122:123]
	v_pk_mul_f32 v[124:125], v[116:117], v[124:125]
	v_cvt_pk_bf16_f32 v114, v118, v119
	v_cvt_pk_bf16_f32 v115, v120, v121
	v_cvt_pk_bf16_f32 v116, v122, v123
	v_cvt_pk_bf16_f32 v117, v124, v125
	global_store_dwordx4 v[236:237], v[114:117], off
	v_mov_b32_e32 v188, v229
	v_pk_mul_f32 v[110:111], v[110:111], v[188:189] op_sel_hi:[1,0]
	v_pk_mul_f32 v[112:113], v[112:113], v[188:189] op_sel_hi:[1,0]
	v_pk_mul_f32 v[106:107], v[106:107], v[188:189] op_sel_hi:[1,0]
	v_pk_mul_f32 v[108:109], v[108:109], v[188:189] op_sel_hi:[1,0]
	v_pk_mul_f32 v[176:177], v[110:111], v[184:185] op_sel_hi:[1,0]
	v_pk_mul_f32 v[178:179], v[112:113], v[184:185] op_sel_hi:[1,0]
	v_pk_mul_f32 v[180:181], v[106:107], v[184:185] op_sel_hi:[1,0]
	v_pk_mul_f32 v[182:183], v[108:109], v[184:185] op_sel_hi:[1,0]
	v_exp_f32_e32 v176, v176
	v_exp_f32_e32 v177, v177
	v_exp_f32_e32 v178, v178
	v_exp_f32_e32 v179, v179
	v_exp_f32_e32 v180, v180
	v_exp_f32_e32 v181, v181
	v_exp_f32_e32 v182, v182
	v_exp_f32_e32 v183, v183
	v_pk_add_f32 v[176:177], v[176:177], v[186:187] op_sel_hi:[1,0]
	v_pk_add_f32 v[178:179], v[178:179], v[186:187] op_sel_hi:[1,0]
	v_pk_add_f32 v[180:181], v[180:181], v[186:187] op_sel_hi:[1,0]
	v_pk_add_f32 v[182:183], v[182:183], v[186:187] op_sel_hi:[1,0]
	v_rcp_f32_e32 v176, v176
	v_rcp_f32_e32 v177, v177
	v_rcp_f32_e32 v178, v178
	v_rcp_f32_e32 v179, v179
	v_rcp_f32_e32 v180, v180
	v_rcp_f32_e32 v181, v181
	v_rcp_f32_e32 v182, v182
	v_rcp_f32_e32 v183, v183
	v_pk_mul_f32 v[102:103], v[102:103], v[188:189] op_sel_hi:[1,0]
	v_pk_mul_f32 v[104:105], v[104:105], v[188:189] op_sel_hi:[1,0]
	v_pk_mul_f32 v[98:99], v[98:99], v[188:189] op_sel_hi:[1,0]
	v_pk_mul_f32 v[100:101], v[100:101], v[188:189] op_sel_hi:[1,0]
	v_pk_mul_f32 v[110:111], v[110:111], v[176:177]
	v_pk_mul_f32 v[112:113], v[112:113], v[178:179]
	v_pk_mul_f32 v[106:107], v[106:107], v[180:181]
	v_pk_mul_f32 v[108:109], v[108:109], v[182:183]
	v_pk_mul_f32 v[102:103], v[102:103], v[110:111]
	v_pk_mul_f32 v[104:105], v[104:105], v[112:113]
	v_pk_mul_f32 v[106:107], v[98:99], v[106:107]
	v_pk_mul_f32 v[108:109], v[100:101], v[108:109]
	v_cvt_pk_bf16_f32 v98, v102, v103
	v_cvt_pk_bf16_f32 v99, v104, v105
	v_cvt_pk_bf16_f32 v100, v106, v107
	v_cvt_pk_bf16_f32 v101, v108, v109
	v_lshl_add_u64 v[236:237], v[236:237], 0, s[100:101]
	global_store_dwordx4 v[236:237], v[98:101], off
	v_pk_mul_f32 v[94:95], v[94:95], v[230:231] op_sel_hi:[1,0]
	v_pk_mul_f32 v[96:97], v[96:97], v[230:231] op_sel_hi:[1,0]
	v_pk_mul_f32 v[90:91], v[90:91], v[230:231] op_sel_hi:[1,0]
	v_pk_mul_f32 v[92:93], v[92:93], v[230:231] op_sel_hi:[1,0]
	v_pk_mul_f32 v[176:177], v[94:95], v[184:185] op_sel_hi:[1,0]
	v_pk_mul_f32 v[178:179], v[96:97], v[184:185] op_sel_hi:[1,0]
	v_pk_mul_f32 v[180:181], v[90:91], v[184:185] op_sel_hi:[1,0]
	v_pk_mul_f32 v[182:183], v[92:93], v[184:185] op_sel_hi:[1,0]
	v_exp_f32_e32 v176, v176
	v_exp_f32_e32 v177, v177
	v_exp_f32_e32 v178, v178
	v_exp_f32_e32 v179, v179
	v_exp_f32_e32 v180, v180
	v_exp_f32_e32 v181, v181
	v_exp_f32_e32 v182, v182
	v_exp_f32_e32 v183, v183
	v_pk_add_f32 v[176:177], v[176:177], v[186:187] op_sel_hi:[1,0]
	v_pk_add_f32 v[178:179], v[178:179], v[186:187] op_sel_hi:[1,0]
	v_pk_add_f32 v[180:181], v[180:181], v[186:187] op_sel_hi:[1,0]
	v_pk_add_f32 v[182:183], v[182:183], v[186:187] op_sel_hi:[1,0]
	v_rcp_f32_e32 v176, v176
	v_rcp_f32_e32 v177, v177
	v_rcp_f32_e32 v178, v178
; __device__ __forceinline__ unsigned cvt_pk_bf16(float lo, float hi) { f32x2 v = {lo, hi}; return __builtin_bit_cast(unsigned, __builtin_convertvector(v, nbf16x2e)); }
;     __device__ __forceinline__ void operator()(const f32x4 (&acc)[2][2][4][2], const Unit& u, int wr, int wc, int fr, int fq) const {
;     ...
;         for (int ai = 0; ai < 2; ++ai)
; #pragma unroll
;             for (int m = 0; m < 4; ++m) {
;                 const int row = row0 + ai * HALF + m * 16;
;                 float rs;
;                 if (rsc) rs = rsc[row - rbase];
;                 else {
;                     const f32x4* pp = (const f32x4*)(part + (size_t)row * 16);
;                     const f32x4 p0 = pp[0], p1 = pp[1], p2 = pp[2], p3 = pp[3];
;                     const float ssq = ((p0[0] + p0[1]) + (p0[2] + p0[3])) + ((p1[0] + p1[1]) + (p1[2] + p1[3])) + ((p2[0] + p2[1]) + (p2[2] + p2[3])) + ((p3[0] + p3[1]) + (p3[2] + p3[3]));
;                     rs = __builtin_amdgcn_rsqf(ssq * (1.0f / 1024.0f) + 1e-6f);
;                 }
;                 float v[8];
; #pragma unroll
;                 for (int n = 0; n < 2; ++n)
; #pragma unroll
;                     for (int i = 0; i < 4; ++i) { const float g = acc[ai][0][m][n][i] * rs, up = acc[ai][1][m][n][i] * rs; v[4 * n + i] = g * __builtin_amdgcn_rcpf(1.0f + __expf(-g)) * up; }
;                 u32x4 w; w.x = cvt_pk_bf16(v[0], v[1]); w.y = cvt_pk_bf16(v[2], v[3]); w.z = cvt_pk_bf16(v[4], v[5]); w.w = cvt_pk_bf16(v[6], v[7]);
;                 *(u32x4*)(O + (size_t)row * 2816 + u.pn * HALF + wc * 32 + 8 * fq) = w;
	v_rcp_f32_e32 v179, v179
	v_rcp_f32_e32 v180, v180
	v_rcp_f32_e32 v181, v181
	v_rcp_f32_e32 v182, v182
	v_rcp_f32_e32 v183, v183
	v_pk_mul_f32 v[86:87], v[86:87], v[230:231] op_sel_hi:[1,0]
	v_pk_mul_f32 v[88:89], v[88:89], v[230:231] op_sel_hi:[1,0]
	v_pk_mul_f32 v[82:83], v[82:83], v[230:231] op_sel_hi:[1,0]
	v_pk_mul_f32 v[84:85], v[84:85], v[230:231] op_sel_hi:[1,0]
	v_pk_mul_f32 v[94:95], v[94:95], v[176:177]
	v_pk_mul_f32 v[96:97], v[96:97], v[178:179]
	v_pk_mul_f32 v[90:91], v[90:91], v[180:181]
	v_pk_mul_f32 v[92:93], v[92:93], v[182:183]
	v_pk_mul_f32 v[86:87], v[86:87], v[94:95]
	v_pk_mul_f32 v[88:89], v[88:89], v[96:97]
	v_pk_mul_f32 v[90:91], v[82:83], v[90:91]
	v_pk_mul_f32 v[92:93], v[84:85], v[92:93]
	v_cvt_pk_bf16_f32 v82, v86, v87
	v_cvt_pk_bf16_f32 v83, v88, v89
	v_cvt_pk_bf16_f32 v84, v90, v91
	v_cvt_pk_bf16_f32 v85, v92, v93
	v_lshl_add_u64 v[236:237], v[236:237], 0, s[100:101]
	global_store_dwordx4 v[236:237], v[82:85], off
	v_mov_b32_e32 v188, v231
	v_pk_mul_f32 v[78:79], v[78:79], v[188:189] op_sel_hi:[1,0]
	v_pk_mul_f32 v[80:81], v[80:81], v[188:189] op_sel_hi:[1,0]
	v_pk_mul_f32 v[74:75], v[74:75], v[188:189] op_sel_hi:[1,0]
	v_pk_mul_f32 v[76:77], v[76:77], v[188:189] op_sel_hi:[1,0]
	v_pk_mul_f32 v[176:177], v[78:79], v[184:185] op_sel_hi:[1,0]
	v_pk_mul_f32 v[178:179], v[80:81], v[184:185] op_sel_hi:[1,0]
	v_pk_mul_f32 v[180:181], v[74:75], v[184:185] op_sel_hi:[1,0]
	v_pk_mul_f32 v[182:183], v[76:77], v[184:185] op_sel_hi:[1,0]
	v_exp_f32_e32 v176, v176
	v_exp_f32_e32 v177, v177
	v_exp_f32_e32 v178, v178
	v_exp_f32_e32 v179, v179
	v_exp_f32_e32 v180, v180
	v_exp_f32_e32 v181, v181
	v_exp_f32_e32 v182, v182
	v_exp_f32_e32 v183, v183
	v_pk_add_f32 v[176:177], v[176:177], v[186:187] op_sel_hi:[1,0]
	v_pk_add_f32 v[178:179], v[178:179], v[186:187] op_sel_hi:[1,0]
	v_pk_add_f32 v[180:181], v[180:181], v[186:187] op_sel_hi:[1,0]
	v_pk_add_f32 v[182:183], v[182:183], v[186:187] op_sel_hi:[1,0]
	v_rcp_f32_e32 v176, v176
	v_rcp_f32_e32 v177, v177
	v_rcp_f32_e32 v178, v178
	v_rcp_f32_e32 v179, v179
	v_rcp_f32_e32 v180, v180
	v_rcp_f32_e32 v181, v181
	v_rcp_f32_e32 v182, v182
	v_rcp_f32_e32 v183, v183
	v_pk_mul_f32 v[70:71], v[70:71], v[188:189] op_sel_hi:[1,0]
	v_pk_mul_f32 v[72:73], v[72:73], v[188:189] op_sel_hi:[1,0]
	v_pk_mul_f32 v[66:67], v[66:67], v[188:189] op_sel_hi:[1,0]
	v_pk_mul_f32 v[68:69], v[68:69], v[188:189] op_sel_hi:[1,0]
	v_pk_mul_f32 v[78:79], v[78:79], v[176:177]
	v_pk_mul_f32 v[80:81], v[80:81], v[178:179]
	v_pk_mul_f32 v[74:75], v[74:75], v[180:181]
	v_pk_mul_f32 v[76:77], v[76:77], v[182:183]
	v_pk_mul_f32 v[70:71], v[70:71], v[78:79]
	v_pk_mul_f32 v[72:73], v[72:73], v[80:81]
	v_pk_mul_f32 v[74:75], v[66:67], v[74:75]
	v_pk_mul_f32 v[76:77], v[68:69], v[76:77]
	v_cvt_pk_bf16_f32 v66, v70, v71
	v_cvt_pk_bf16_f32 v67, v72, v73
	v_cvt_pk_bf16_f32 v68, v74, v75
	v_cvt_pk_bf16_f32 v69, v76, v77
	v_lshl_add_u64 v[236:237], v[236:237], 0, s[100:101]
	global_store_dwordx4 v[236:237], v[66:69], off
	v_pk_mul_f32 v[62:63], v[62:63], v[232:233] op_sel_hi:[1,0]
	v_pk_mul_f32 v[64:65], v[64:65], v[232:233] op_sel_hi:[1,0]
	v_pk_mul_f32 v[58:59], v[58:59], v[232:233] op_sel_hi:[1,0]
	v_pk_mul_f32 v[60:61], v[60:61], v[232:233] op_sel_hi:[1,0]
	v_pk_mul_f32 v[176:177], v[62:63], v[184:185] op_sel_hi:[1,0]
	v_pk_mul_f32 v[178:179], v[64:65], v[184:185] op_sel_hi:[1,0]
	v_pk_mul_f32 v[180:181], v[58:59], v[184:185] op_sel_hi:[1,0]
	v_pk_mul_f32 v[182:183], v[60:61], v[184:185] op_sel_hi:[1,0]
	v_exp_f32_e32 v176, v176
	v_exp_f32_e32 v177, v177
	v_exp_f32_e32 v178, v178
	v_exp_f32_e32 v179, v179
	v_exp_f32_e32 v180, v180
	v_exp_f32_e32 v181, v181
	v_exp_f32_e32 v182, v182
	v_exp_f32_e32 v183, v183
	v_pk_add_f32 v[176:177], v[176:177], v[186:187] op_sel_hi:[1,0]
	v_pk_add_f32 v[178:179], v[178:179], v[186:187] op_sel_hi:[1,0]
	v_pk_add_f32 v[180:181], v[180:181], v[186:187] op_sel_hi:[1,0]
	v_pk_add_f32 v[182:183], v[182:183], v[186:187] op_sel_hi:[1,0]
	v_rcp_f32_e32 v176, v176
	v_rcp_f32_e32 v177, v177
	v_rcp_f32_e32 v178, v178
	v_rcp_f32_e32 v179, v179
	v_rcp_f32_e32 v180, v180
	v_rcp_f32_e32 v181, v181
	v_rcp_f32_e32 v182, v182
	v_rcp_f32_e32 v183, v183
	v_pk_mul_f32 v[54:55], v[54:55], v[232:233] op_sel_hi:[1,0]
	v_pk_mul_f32 v[56:57], v[56:57], v[232:233] op_sel_hi:[1,0]
	v_pk_mul_f32 v[50:51], v[50:51], v[232:233] op_sel_hi:[1,0]
	v_pk_mul_f32 v[52:53], v[52:53], v[232:233] op_sel_hi:[1,0]
	v_pk_mul_f32 v[62:63], v[62:63], v[176:177]
	v_pk_mul_f32 v[64:65], v[64:65], v[178:179]
	v_pk_mul_f32 v[58:59], v[58:59], v[180:181]
	v_pk_mul_f32 v[60:61], v[60:61], v[182:183]
	v_pk_mul_f32 v[54:55], v[54:55], v[62:63]
	v_pk_mul_f32 v[56:57], v[56:57], v[64:65]
	v_pk_mul_f32 v[58:59], v[50:51], v[58:59]
	v_pk_mul_f32 v[60:61], v[52:53], v[60:61]
	v_cvt_pk_bf16_f32 v50, v54, v55
	v_cvt_pk_bf16_f32 v51, v56, v57
	v_cvt_pk_bf16_f32 v52, v58, v59
	v_cvt_pk_bf16_f32 v53, v60, v61
	v_lshl_add_u64 v[236:237], v[236:237], 0, s[98:99]
	global_store_dwordx4 v[236:237], v[50:53], off
	v_mov_b32_e32 v188, v233
	v_pk_mul_f32 v[46:47], v[46:47], v[188:189] op_sel_hi:[1,0]
	v_pk_mul_f32 v[48:49], v[48:49], v[188:189] op_sel_hi:[1,0]
	v_pk_mul_f32 v[42:43], v[42:43], v[188:189] op_sel_hi:[1,0]
	v_pk_mul_f32 v[44:45], v[44:45], v[188:189] op_sel_hi:[1,0]
	v_pk_mul_f32 v[176:177], v[46:47], v[184:185] op_sel_hi:[1,0]
	v_pk_mul_f32 v[178:179], v[48:49], v[184:185] op_sel_hi:[1,0]
	v_pk_mul_f32 v[180:181], v[42:43], v[184:185] op_sel_hi:[1,0]
	v_pk_mul_f32 v[182:183], v[44:45], v[184:185] op_sel_hi:[1,0]
	v_exp_f32_e32 v176, v176
; __device__ __forceinline__ unsigned cvt_pk_bf16(float lo, float hi) { f32x2 v = {lo, hi}; return __builtin_bit_cast(unsigned, __builtin_convertvector(v, nbf16x2e)); }
;     __device__ __forceinline__ void operator()(const f32x4 (&acc)[2][2][4][2], const Unit& u, int wr, int wc, int fr, int fq) const {
;     ...
;         for (int ai = 0; ai < 2; ++ai)
; #pragma unroll
;             for (int m = 0; m < 4; ++m) {
;                 const int row = row0 + ai * HALF + m * 16;
;                 float rs;
;                 if (rsc) rs = rsc[row - rbase];
;                 else {
;                     const f32x4* pp = (const f32x4*)(part + (size_t)row * 16);
;                     const f32x4 p0 = pp[0], p1 = pp[1], p2 = pp[2], p3 = pp[3];
;                     const float ssq = ((p0[0] + p0[1]) + (p0[2] + p0[3])) + ((p1[0] + p1[1]) + (p1[2] + p1[3])) + ((p2[0] + p2[1]) + (p2[2] + p2[3])) + ((p3[0] + p3[1]) + (p3[2] + p3[3]));
;                     rs = __builtin_amdgcn_rsqf(ssq * (1.0f / 1024.0f) + 1e-6f);
;                 }
;                 float v[8];
; #pragma unroll
;                 for (int n = 0; n < 2; ++n)
; #pragma unroll
;                     for (int i = 0; i < 4; ++i) { const float g = acc[ai][0][m][n][i] * rs, up = acc[ai][1][m][n][i] * rs; v[4 * n + i] = g * __builtin_amdgcn_rcpf(1.0f + __expf(-g)) * up; }
;                 u32x4 w; w.x = cvt_pk_bf16(v[0], v[1]); w.y = cvt_pk_bf16(v[2], v[3]); w.z = cvt_pk_bf16(v[4], v[5]); w.w = cvt_pk_bf16(v[6], v[7]);
;                 *(u32x4*)(O + (size_t)row * 2816 + u.pn * HALF + wc * 32 + 8 * fq) = w;
	v_exp_f32_e32 v177, v177
	v_exp_f32_e32 v178, v178
	v_exp_f32_e32 v179, v179
	v_exp_f32_e32 v180, v180
	v_exp_f32_e32 v181, v181
	v_exp_f32_e32 v182, v182
	v_exp_f32_e32 v183, v183
	v_pk_add_f32 v[176:177], v[176:177], v[186:187] op_sel_hi:[1,0]
	v_pk_add_f32 v[178:179], v[178:179], v[186:187] op_sel_hi:[1,0]
	v_pk_add_f32 v[180:181], v[180:181], v[186:187] op_sel_hi:[1,0]
	v_pk_add_f32 v[182:183], v[182:183], v[186:187] op_sel_hi:[1,0]
	v_rcp_f32_e32 v176, v176
	v_rcp_f32_e32 v177, v177
	v_rcp_f32_e32 v178, v178
	v_rcp_f32_e32 v179, v179
	v_rcp_f32_e32 v180, v180
	v_rcp_f32_e32 v181, v181
	v_rcp_f32_e32 v182, v182
	v_rcp_f32_e32 v183, v183
	v_pk_mul_f32 v[38:39], v[38:39], v[188:189] op_sel_hi:[1,0]
	v_pk_mul_f32 v[40:41], v[40:41], v[188:189] op_sel_hi:[1,0]
	v_pk_mul_f32 v[34:35], v[34:35], v[188:189] op_sel_hi:[1,0]
	v_pk_mul_f32 v[36:37], v[36:37], v[188:189] op_sel_hi:[1,0]
	v_pk_mul_f32 v[46:47], v[46:47], v[176:177]
	v_pk_mul_f32 v[48:49], v[48:49], v[178:179]
	v_pk_mul_f32 v[42:43], v[42:43], v[180:181]
	v_pk_mul_f32 v[44:45], v[44:45], v[182:183]
	v_pk_mul_f32 v[38:39], v[38:39], v[46:47]
	v_pk_mul_f32 v[40:41], v[40:41], v[48:49]
	v_pk_mul_f32 v[42:43], v[34:35], v[42:43]
	v_pk_mul_f32 v[44:45], v[36:37], v[44:45]
	v_cvt_pk_bf16_f32 v34, v38, v39
	v_cvt_pk_bf16_f32 v35, v40, v41
	v_cvt_pk_bf16_f32 v36, v42, v43
	v_cvt_pk_bf16_f32 v37, v44, v45
	v_lshl_add_u64 v[236:237], v[236:237], 0, s[100:101]
	global_store_dwordx4 v[236:237], v[34:37], off
	v_pk_mul_f32 v[30:31], v[30:31], v[234:235] op_sel_hi:[1,0]
	v_pk_mul_f32 v[32:33], v[32:33], v[234:235] op_sel_hi:[1,0]
	v_pk_mul_f32 v[26:27], v[26:27], v[234:235] op_sel_hi:[1,0]
	v_pk_mul_f32 v[28:29], v[28:29], v[234:235] op_sel_hi:[1,0]
	v_pk_mul_f32 v[176:177], v[30:31], v[184:185] op_sel_hi:[1,0]
	v_pk_mul_f32 v[178:179], v[32:33], v[184:185] op_sel_hi:[1,0]
	v_pk_mul_f32 v[180:181], v[26:27], v[184:185] op_sel_hi:[1,0]
	v_pk_mul_f32 v[182:183], v[28:29], v[184:185] op_sel_hi:[1,0]
	v_exp_f32_e32 v176, v176
	v_exp_f32_e32 v177, v177
	v_exp_f32_e32 v178, v178
	v_exp_f32_e32 v179, v179
	v_exp_f32_e32 v180, v180
	v_exp_f32_e32 v181, v181
	v_exp_f32_e32 v182, v182
	v_exp_f32_e32 v183, v183
	v_pk_add_f32 v[176:177], v[176:177], v[186:187] op_sel_hi:[1,0]
	v_pk_add_f32 v[178:179], v[178:179], v[186:187] op_sel_hi:[1,0]
	v_pk_add_f32 v[180:181], v[180:181], v[186:187] op_sel_hi:[1,0]
	v_pk_add_f32 v[182:183], v[182:183], v[186:187] op_sel_hi:[1,0]
	v_rcp_f32_e32 v176, v176
	v_rcp_f32_e32 v177, v177
	v_rcp_f32_e32 v178, v178
	v_rcp_f32_e32 v179, v179
	v_rcp_f32_e32 v180, v180
	v_rcp_f32_e32 v181, v181
	v_rcp_f32_e32 v182, v182
	v_rcp_f32_e32 v183, v183
	v_pk_mul_f32 v[22:23], v[22:23], v[234:235] op_sel_hi:[1,0]
	v_pk_mul_f32 v[24:25], v[24:25], v[234:235] op_sel_hi:[1,0]
	v_pk_mul_f32 v[18:19], v[18:19], v[234:235] op_sel_hi:[1,0]
	v_pk_mul_f32 v[20:21], v[20:21], v[234:235] op_sel_hi:[1,0]
	v_pk_mul_f32 v[30:31], v[30:31], v[176:177]
	v_pk_mul_f32 v[32:33], v[32:33], v[178:179]
	v_pk_mul_f32 v[26:27], v[26:27], v[180:181]
	v_pk_mul_f32 v[28:29], v[28:29], v[182:183]
	v_pk_mul_f32 v[22:23], v[22:23], v[30:31]
	v_pk_mul_f32 v[24:25], v[24:25], v[32:33]
	v_pk_mul_f32 v[26:27], v[18:19], v[26:27]
	v_pk_mul_f32 v[28:29], v[20:21], v[28:29]
	v_cvt_pk_bf16_f32 v18, v22, v23
	v_cvt_pk_bf16_f32 v19, v24, v25
	v_cvt_pk_bf16_f32 v20, v26, v27
	v_cvt_pk_bf16_f32 v21, v28, v29
	v_lshl_add_u64 v[236:237], v[236:237], 0, s[100:101]
	global_store_dwordx4 v[236:237], v[18:21], off
	v_mov_b32_e32 v188, v235
	v_pk_mul_f32 v[14:15], v[14:15], v[188:189] op_sel_hi:[1,0]
	v_pk_mul_f32 v[16:17], v[16:17], v[188:189] op_sel_hi:[1,0]
	v_pk_mul_f32 v[10:11], v[10:11], v[188:189] op_sel_hi:[1,0]
	v_pk_mul_f32 v[12:13], v[12:13], v[188:189] op_sel_hi:[1,0]
	v_pk_mul_f32 v[176:177], v[14:15], v[184:185] op_sel_hi:[1,0]
	v_pk_mul_f32 v[178:179], v[16:17], v[184:185] op_sel_hi:[1,0]
	v_pk_mul_f32 v[180:181], v[10:11], v[184:185] op_sel_hi:[1,0]
	v_pk_mul_f32 v[182:183], v[12:13], v[184:185] op_sel_hi:[1,0]
	v_exp_f32_e32 v176, v176
	v_exp_f32_e32 v177, v177
	v_exp_f32_e32 v178, v178
	v_exp_f32_e32 v179, v179
	v_exp_f32_e32 v180, v180
	v_exp_f32_e32 v181, v181
	v_exp_f32_e32 v182, v182
	v_exp_f32_e32 v183, v183
	v_pk_add_f32 v[176:177], v[176:177], v[186:187] op_sel_hi:[1,0]
	v_pk_add_f32 v[178:179], v[178:179], v[186:187] op_sel_hi:[1,0]
	v_pk_add_f32 v[180:181], v[180:181], v[186:187] op_sel_hi:[1,0]
	v_pk_add_f32 v[182:183], v[182:183], v[186:187] op_sel_hi:[1,0]
	v_rcp_f32_e32 v176, v176
	v_rcp_f32_e32 v177, v177
	v_rcp_f32_e32 v178, v178
	v_rcp_f32_e32 v179, v179
	v_rcp_f32_e32 v180, v180
	v_rcp_f32_e32 v181, v181
	v_rcp_f32_e32 v182, v182
	v_rcp_f32_e32 v183, v183
	v_pk_mul_f32 v[6:7], v[6:7], v[188:189] op_sel_hi:[1,0]
	v_pk_mul_f32 v[8:9], v[8:9], v[188:189] op_sel_hi:[1,0]
	v_pk_mul_f32 v[2:3], v[2:3], v[188:189] op_sel_hi:[1,0]
	v_pk_mul_f32 v[4:5], v[4:5], v[188:189] op_sel_hi:[1,0]
	v_pk_mul_f32 v[14:15], v[14:15], v[176:177]
	v_pk_mul_f32 v[16:17], v[16:17], v[178:179]
	v_pk_mul_f32 v[10:11], v[10:11], v[180:181]
	v_pk_mul_f32 v[12:13], v[12:13], v[182:183]
	v_pk_mul_f32 v[6:7], v[6:7], v[14:15]
	v_pk_mul_f32 v[8:9], v[8:9], v[16:17]
	v_pk_mul_f32 v[10:11], v[2:3], v[10:11]
	v_pk_mul_f32 v[12:13], v[4:5], v[12:13]
	v_cvt_pk_bf16_f32 v2, v6, v7
	v_cvt_pk_bf16_f32 v3, v8, v9
	v_cvt_pk_bf16_f32 v4, v10, v11
	v_cvt_pk_bf16_f32 v5, v12, v13
	v_lshl_add_u64 v[236:237], v[236:237], 0, s[100:101]
	s_andn2_b64 vcc, exec, s[0:1]
	s_mov_b64 s[0:1], -1
	global_store_dwordx4 v[236:237], v[2:5], off
	s_branch .Lgu_done
